# waits moved to first consumer: attention block prologue no longer drains Q loads before issuing tile-0 DMA; counted vmcnt at in-proj/gate-up epilogue start
# baseline (speedup 1.0000x reference)
;     __device__ __forceinline__ void a_ready(const Unit& u) const {
;         const float* p = rsv + u.pm * BM + wr_ * 64 + lane_;
;         if (n_ready & 1) { b0 = p[0]; b1 = p[HALF]; } else { a0 = p[0]; a1 = p[HALF]; }
;         ++n_ready;
;     }
;     __device__ __forceinline__ void operator()(const f32x4 (&acc)[2][2][4][2], const Unit& u, int wr, int wc, int fr, int fq) const {
;         const int row0 = u.pm * BM + wr * 64 + fr;
;         const bool par = (n_done & 1) != 0; ++n_done;
;         const float r0 = par ? S->b0 : S->a0, r1 = par ? S->b1 : S->a1;
;         float rs8[8];
; #pragma unroll
;         for (int i = 0; i < 8; ++i) rs8[i] = __builtin_bit_cast(float, __builtin_amdgcn_ds_bpermute(((i & 3) * 16 + fr) << 2, __builtin_bit_cast(int, (i >> 2) ? r1 : r0)));
.LBB0_187:
	s_bitcmp0_b32 s93, 0
	s_cselect_b64 vcc, -1, 0
	s_waitcnt vmcnt(8)
	s_and_b64 s[68:69], s[2:3], exec
	s_cbranch_scc0 .Lp1_noar
	s_bitcmp1_b32 s93, 0
	s_cbranch_scc1 .Lp1_ar_a
	global_load_dword v191, v[156:157], off
	global_load_dword v190, v[156:157], off offset:512
	s_branch .Lp1_noar

; #define ATT_WAIT_V(n) asm volatile("s_waitcnt vmcnt(" #n ")" ::: "memory")
; __device__ __forceinline__ void attn_block(LAS unsigned char* lds, const Ptrs& P, int b, int h, int qb, float negMb, float lam, int tid, int wid, int lane) {
;     ...
;     const int qpos = qb * 128 + quarter * 32 + l31;
;     bf16x8 qf[8];
;     { const bf16* qp = P.Q + (tok0 + qpos) * 1024 + h * 256 + comp * 128 + hh * 8;
; #pragma unroll
;       for (int ks = 0; ks < 8; ++ks) qf[ks] = *(const bf16x8*)(qp + ks * 16); }
;     const unsigned ldsw = (unsigned)wid * 4096u;
;     const unsigned lds0 = (unsigned)__builtin_amdgcn_readfirstlane((int)(unsigned)(uintptr_t)lds);
;     unsigned kb0, kx16, vb0, vy16;
;     { int ln_ = lane; asm volatile("" : "+v"(ln_));
;       kb0 = (unsigned)(((16 * (wid & 3) + (ln_ >> 4)) * 1024 + h * 256 + (wid >> 2) * 128) * 2); kx16 = (unsigned)(((ln_ & 15) ^ (ln_ >> 4)) << 4);
;       vb0 = (unsigned)(((h * 256 + 32 * wid + (ln_ >> 3)) * M_TOK) * 2); vy16 = (unsigned)(((ln_ & 7) ^ (ln_ >> 4)) << 4);
;       asm volatile("" : "+v"(kb0), "+v"(kx16), "+v"(vb0), "+v"(vy16)); }
;     ...
;     f32x16 o[8];
; #pragma unroll
;     for (int e = 0; e < 8; ++e)
; #pragma unroll
;         for (int r = 0; r < 16; ++r) o[e][r] = 0.f;
;     float lsum = 0.f;
;     ATT_WAIT_V(0);
; #pragma unroll
;     for (int ks = 0; ks < 8; ++ks) asm volatile("" : "+v"(qf[ks]));
;     ATT_DMA(0, 0);
.LBB0_413:
	s_xor_b64 s[40:41], s[0:1], -1
	s_and_b64 s[0:1], s[0:1], exec
	s_cselect_b32 s2, s78, s77
	s_lshl_b32 s80, s2, 7
	s_add_i32 s80, s80, s50
	v_or_b32_e32 v194, s80, v203
	v_lshl_add_u64 v[18:19], s[20:21], 0, v[194:195]
	v_lshlrev_b64 v[18:19], 11, v[18:19]
	v_lshl_add_u64 v[18:19], v[198:199], 0, v[18:19]
	flat_load_dwordx4 v[190:193], v[18:19]
	flat_load_dwordx4 v[186:189], v[18:19] offset:32
	flat_load_dwordx4 v[182:185], v[18:19] offset:64
	flat_load_dwordx4 v[178:181], v[18:19] offset:96
	flat_load_dwordx4 v[174:177], v[18:19] offset:128
	flat_load_dwordx4 v[166:169], v[18:19] offset:160
	flat_load_dwordx4 v[170:173], v[18:19] offset:192
	flat_load_dwordx4 v[162:165], v[18:19] offset:224
	v_mov_b32_e32 v51, v1
	s_lshl_b32 s82, s2, 17
	v_ashrrev_i32_e32 v52, 4, v51
	v_lshrrev_b32_e32 v53, 3, v51
	v_add_u32_e32 v54, s51, v52
	v_bitop3_b32 v55, v51, v52, 15 bitop3:0x6c
	v_bitop3_b32 v51, v51, v52, 7 bitop3:0x6c
	v_add_lshl_u32 v53, s79, v53, 16
	v_lshl_add_u32 v52, v54, 11, s4
	v_lshlrev_b32_e32 v54, 4, v55
	v_lshlrev_b32_e32 v51, 4, v51
	s_nop 0
	v_mov_b32_e32 v194, 0
	v_add_u32_e32 v206, v52, v54
	v_xor_b32_e32 v55, 64, v54
	v_xor_b32_e32 v56, 0x80, v54
	v_add3_u32 v208, v52, v55, s71
	v_xor_b32_e32 v54, 0xc0, v54
	v_add3_u32 v209, v52, v56, s72
	v_add3_u32 v210, v52, v54, s73
	v_add_u32_e32 v207, v53, v51
	v_xad_u32 v51, v51, 64, v53
	v_add_u32_e32 v211, 0x80000, v51
	v_add_u32_e32 v212, 0x100000, v207
	v_add_u32_e32 v213, 0x180000, v51
	s_mov_b32 s81, 0
	s_mov_b64 s[0:1], s[38:39]
	s_mov_b64 s[42:43], s[36:37]
	v_mov_b32_e32 v18, 0
	v_mov_b32_e32 v34, 0
	v_mov_b32_e32 v50, 0
	v_mov_b32_e32 v19, v194
	v_mov_b32_e32 v20, v194
	v_mov_b32_e32 v21, v194
	v_mov_b32_e32 v22, v194
	v_mov_b32_e32 v23, v194
	v_mov_b32_e32 v24, v194
	v_mov_b32_e32 v25, v194
	v_mov_b32_e32 v26, v194
	v_mov_b32_e32 v27, v194
	v_mov_b32_e32 v28, v194
	v_mov_b32_e32 v29, v194
	v_mov_b32_e32 v30, v194
	v_mov_b32_e32 v31, v194
	v_mov_b32_e32 v32, v194
	v_mov_b32_e32 v33, v194
	v_mov_b32_e32 v35, v194
	v_mov_b32_e32 v36, v194
	v_mov_b32_e32 v37, v194
	v_mov_b32_e32 v38, v194
	v_mov_b32_e32 v39, v194
	v_mov_b32_e32 v40, v194
	v_mov_b32_e32 v41, v194
	v_mov_b32_e32 v42, v194
	v_mov_b32_e32 v43, v194
	v_mov_b32_e32 v44, v194
	v_mov_b32_e32 v45, v194
	v_mov_b32_e32 v46, v194
	v_mov_b32_e32 v47, v194
	v_mov_b32_e32 v48, v194
	v_mov_b32_e32 v49, v194
	s_bitset1_b32 s82, 16
	v_mov_b32_e32 v51, v194
	v_mov_b32_e32 v52, v194
	v_mov_b32_e32 v53, v194
	v_mov_b32_e32 v54, v194
	v_mov_b32_e32 v55, v194
	v_mov_b32_e32 v56, v194
	v_mov_b32_e32 v57, v194
	v_mov_b32_e32 v58, v194
	s_nop 0
	s_mov_b32 s2, m0
	s_mov_b32 m0, s54
	s_nop 0
	global_load_lds_dwordx4 v206, s[24:25]
	s_mov_b32 m0, s2
	v_mov_b32_e32 v59, v194
	s_mov_b32 s2, m0
	s_mov_b32 m0, s55
	s_nop 0
	global_load_lds_dwordx4 v208, s[24:25]
	s_mov_b32 m0, s2
	v_mov_b32_e32 v60, v194
	s_mov_b32 s2, m0
	s_mov_b32 m0, s56
	s_nop 0
	global_load_lds_dwordx4 v209, s[24:25]
	s_mov_b32 m0, s2
	v_mov_b32_e32 v61, v194
	s_mov_b32 s2, m0
	s_mov_b32 m0, s57
	s_nop 0
	global_load_lds_dwordx4 v210, s[24:25]
	s_mov_b32 m0, s2
	v_mov_b32_e32 v62, v194
	s_mov_b32 s2, m0
	s_mov_b32 m0, s61
	s_nop 0
	global_load_lds_dwordx4 v207, s[26:27]
	s_mov_b32 m0, s2
	v_mov_b32_e32 v63, v194
	s_mov_b32 s2, m0
	s_mov_b32 m0, s62
	s_nop 0
	global_load_lds_dwordx4 v211, s[26:27]
	s_mov_b32 m0, s2
	v_mov_b32_e32 v64, v194
	s_mov_b32 s2, m0
	s_mov_b32 m0, s63
	s_nop 0
	global_load_lds_dwordx4 v212, s[26:27]
	s_mov_b32 m0, s2
	v_mov_b32_e32 v65, v194
	s_mov_b32 s2, m0
	s_mov_b32 m0, s64
	s_nop 0
	global_load_lds_dwordx4 v213, s[26:27]
	s_mov_b32 m0, s2
; #define LAS __attribute__((address_space(3)))
; #define LDS_WAIT() asm volatile("s_waitcnt lgkmcnt(0)" ::: "memory")
; __device__ __forceinline__ int pi32(int i) { return (i & ~12) | ((i & 4) << 1) | ((i & 8) >> 1); }
; #define ATT_WAIT_V(n) asm volatile("s_waitcnt vmcnt(" #n ")" ::: "memory")
; #define ATT_BAR() do { asm volatile("" ::: "memory"); __builtin_amdgcn_s_barrier(); asm volatile("" ::: "memory"); } while (0)
; __device__ __forceinline__ void attn_block(LAS unsigned char* lds, const Ptrs& P, int b, int h, int qb, float negMb, float lam, int tid, int wid, int lane) {
;     ...
;     f32x16 o[8];
; #pragma unroll
;     for (int e = 0; e < 8; ++e)
; #pragma unroll
;         for (int r = 0; r < 16; ++r) o[e][r] = 0.f;
;     float lsum = 0.f;
;     ATT_WAIT_V(0);
; #pragma unroll
;     for (int ks = 0; ks < 8; ++ks) asm volatile("" : "+v"(qf[ks]));
;     ATT_DMA(0, 0);
;     const bool early = wid < 4;
;     for (int t = 0; t < NT; ++t) {
;         ATT_WAIT_V(0);
;         LDS_WAIT();
;         ATT_BAR();
;         const bool more = t + 1 < NT;
;         if (more && early) ATT_DMA(t + 1, (t + 1) & 1);
;         const bool active = (quarter >= 2) || more;
;         const LAS unsigned char* base = lds + (t & 1) * BUF;
;         int ln2 = lane; asm volatile("" : "+v"(ln2));
;         const int l31b = ln2 & 31, hhb = ln2 >> 5;
;         const int krow = pi32(l31b), kx = krow & 15;
;         const int koffr = comp * 16384 + krow * 256;
;         const int vx = (l31b >> 1) & 7;
;         const int voffr = V_OFF + l31b * 128;
	v_mov_b32_e32 v66, 0
	v_mov_b32_e32 v67, v194
	v_mov_b32_e32 v68, v194
	v_mov_b32_e32 v69, v194
	v_mov_b32_e32 v70, v194
	v_mov_b32_e32 v71, v194
	v_mov_b32_e32 v72, v194
	v_mov_b32_e32 v73, v194
	v_mov_b32_e32 v74, v194
	v_mov_b32_e32 v75, v194
	v_mov_b32_e32 v76, v194
	v_mov_b32_e32 v77, v194
	v_mov_b32_e32 v78, v194
	v_mov_b32_e32 v79, v194
	v_mov_b32_e32 v80, v194
	v_mov_b32_e32 v81, v194
	v_mov_b32_e32 v82, 0
	v_mov_b32_e32 v83, v194
	v_mov_b32_e32 v84, v194
	v_mov_b32_e32 v85, v194
	v_mov_b32_e32 v86, v194
	v_mov_b32_e32 v87, v194
	v_mov_b32_e32 v88, v194
	v_mov_b32_e32 v89, v194
	v_mov_b32_e32 v90, v194
	v_mov_b32_e32 v91, v194
	v_mov_b32_e32 v92, v194
	v_mov_b32_e32 v93, v194
	v_mov_b32_e32 v94, v194
	v_mov_b32_e32 v95, v194
	v_mov_b32_e32 v96, v194
	v_mov_b32_e32 v97, v194
	v_mov_b32_e32 v98, 0
	v_mov_b32_e32 v99, v194
	v_mov_b32_e32 v100, v194
	v_mov_b32_e32 v101, v194
	v_mov_b32_e32 v102, v194
	v_mov_b32_e32 v103, v194
	v_mov_b32_e32 v104, v194
	v_mov_b32_e32 v105, v194
	v_mov_b32_e32 v106, v194
	v_mov_b32_e32 v107, v194
	v_mov_b32_e32 v108, v194
	v_mov_b32_e32 v109, v194
	v_mov_b32_e32 v110, v194
	v_mov_b32_e32 v111, v194
	v_mov_b32_e32 v112, v194
	v_mov_b32_e32 v113, v194
	v_mov_b32_e32 v114, 0
	v_mov_b32_e32 v115, v194
	v_mov_b32_e32 v116, v194
	v_mov_b32_e32 v117, v194
	v_mov_b32_e32 v118, v194
	v_mov_b32_e32 v119, v194
	v_mov_b32_e32 v120, v194
	v_mov_b32_e32 v121, v194
	v_mov_b32_e32 v122, v194
	v_mov_b32_e32 v123, v194
	v_mov_b32_e32 v124, v194
	v_mov_b32_e32 v125, v194
	v_mov_b32_e32 v126, v194
	v_mov_b32_e32 v127, v194
	v_mov_b32_e32 v128, v194
	v_mov_b32_e32 v129, v194
	v_mov_b32_e32 v130, 0
	v_mov_b32_e32 v131, v194
	v_mov_b32_e32 v132, v194
	v_mov_b32_e32 v133, v194
	v_mov_b32_e32 v134, v194
	v_mov_b32_e32 v135, v194
	v_mov_b32_e32 v136, v194
	v_mov_b32_e32 v137, v194
	v_mov_b32_e32 v138, v194
	v_mov_b32_e32 v139, v194
	v_mov_b32_e32 v140, v194
	v_mov_b32_e32 v141, v194
	v_mov_b32_e32 v142, v194
	v_mov_b32_e32 v143, v194
	v_mov_b32_e32 v144, v194
	v_mov_b32_e32 v145, v194
	v_lshrrev_b32_e32 v226, 5, v1
	v_and_b32_e32 v227, 19, v1
	v_lshlrev_b32_e32 v228, 1, v1
	v_and_b32_e32 v228, 8, v228
	v_lshrrev_b32_e32 v229, 1, v1
	v_and_b32_e32 v230, 4, v229
	v_or3_b32 v227, v227, v228, v230
	v_and_b32_e32 v231, 15, v227
	v_lshl_add_u32 v232, v227, 8, s65
	v_xor_b32_e32 v233, v226, v231
	v_lshl_add_u32 v214, v233, 4, v232
	v_add_u32_e32 v233, 2, v226
	v_xor_b32_e32 v233, v233, v231
	v_lshl_add_u32 v215, v233, 4, v232
	v_add_u32_e32 v233, 4, v226
	v_xor_b32_e32 v233, v233, v231
	v_lshl_add_u32 v216, v233, 4, v232
	v_add_u32_e32 v233, 6, v226
	v_xor_b32_e32 v233, v233, v231
	v_lshl_add_u32 v217, v233, 4, v232
	v_add_u32_e32 v233, 8, v226
	v_xor_b32_e32 v233, v233, v231
	v_lshl_add_u32 v218, v233, 4, v232
	v_add_u32_e32 v233, 10, v226
	v_xor_b32_e32 v233, v233, v231
	v_lshl_add_u32 v219, v233, 4, v232
	v_add_u32_e32 v233, 12, v226
	v_xor_b32_e32 v233, v233, v231
	v_lshl_add_u32 v220, v233, 4, v232
	v_add_u32_e32 v233, 14, v226
	v_xor_b32_e32 v233, v233, v231
	v_lshl_add_u32 v221, v233, 4, v232
	v_and_b32_e32 v234, 7, v229
	v_and_b32_e32 v235, 31, v1
	v_lshlrev_b32_e32 v235, 7, v235
	v_xor_b32_e32 v233, v226, v234
	v_lshl_add_u32 v222, v233, 4, v235
	v_add_u32_e32 v233, 2, v226
	v_xor_b32_e32 v233, v233, v234
	v_lshl_add_u32 v223, v233, 4, v235
	v_add_u32_e32 v233, 4, v226
	v_xor_b32_e32 v233, v233, v234
	v_lshl_add_u32 v224, v233, 4, v235
	v_add_u32_e32 v233, 6, v226
	v_xor_b32_e32 v233, v233, v234
	v_lshl_add_u32 v225, v233, 4, v235
	v_mov_b32_e32 v254, 0
	v_mov_b32_e32 v255, 0
	s_and_b64 vcc, exec, s[12:13]
	s_cbranch_vccz .Lat_noprio
	s_setprio 1

;     __device__ __forceinline__ void a_ready(const Unit& u) const {
;         const float* p = rsv + u.pm * BM + wr_ * 64 + lane_;
;         if (n_ready & 1) { b0 = p[0]; b1 = p[HALF]; } else { a0 = p[0]; a1 = p[HALF]; }
;         ++n_ready;
;     }
;     __device__ __forceinline__ void operator()(const f32x4 (&acc)[2][2][4][2], const Unit& u, int wr, int wc, int fr, int fq) const {
;         const int row0 = u.pm * BM + wr * 64 + fr; bf16_t* base = O + u.pn * 128 + wc * 32 + 8 * fq;
;         const bool par = (n_done & 1) != 0; ++n_done;
;         const float r0 = par ? S->b0 : S->a0, r1 = par ? S->b1 : S->a1;
; #pragma unroll
;         for (int ai = 0; ai < 2; ++ai)
; #pragma unroll
;             for (int m = 0; m < 4; ++m) { const int row = row0 + ai * HALF + m * 16; bf16_t* rowp = base + (size_t)row * ldc;
;                 const float rs = __builtin_bit_cast(float, __builtin_amdgcn_ds_bpermute((m * 16 + fr) << 2, __builtin_bit_cast(int, ai ? r1 : r0)));
.LBB0_697:
	s_lshl_b32 s24, s57, 7
	s_ashr_i32 s25, s24, 31
	s_bitcmp0_b32 s56, 0
	s_cselect_b64 vcc, -1, 0
	s_waitcnt vmcnt(6)
	v_cndmask_b32_e32 v165, v161, v1, vcc
	v_cndmask_b32_e32 v163, v160, v152, vcc
	ds_bpermute_b32 v164, v154, v165
	v_lshl_add_u32 v162, s22, 8, v153
	s_and_b64 vcc, exec, s[2:3]
	s_cbranch_vccz .Lp6_noar
	s_bitcmp1_b32 s56, 0
	s_cbranch_scc1 .Lp6_ar_a
	global_load_dword v161, v[150:151], off
	global_load_dword v160, v[150:151], off offset:512
	s_branch .Lp6_noar
